# attention item epilogue: dwordx4 output stores via permlane32_swap pairs (8 instead of 16 row-per-lane stores per wave), both 1/l lane exchanges issued together
# speedup vs baseline: 1.0139x; 1.0028x over previous
; __device__ __forceinline__ unsigned cvt_pk_bf16(float lo, float hi) { unsigned r; asm("v_cvt_pk_bf16_f32 %0, %1, %2" : "=v"(r) : "v"(lo), "v"(hi)); return r; }
; __device__ __forceinline__ void attn_mfma(PP p, unsigned char* shm, int wv) {
;     ...
; #pragma unroll
;         for (int qi = 0; qi < 2; ++qi) {
;             const float lt = lrun[qi] + __shfl_xor(lrun[qi], 32);
;             const float inv = 1.0f / lt;
;             bf16_t* orow = att + (size_t)(qrow0 + 32 * qi + l31) * 512 + hq * 64;
; #pragma unroll
;             for (int db = 0; db < 2; ++db)
; #pragma unroll
;                 for (int g4 = 0; g4 < 4; ++g4) {
;                     u32x2 w; w.x = cvt_pk_bf16(oacc[db][qi][4 * g4] * inv, oacc[db][qi][4 * g4 + 1] * inv); w.y = cvt_pk_bf16(oacc[db][qi][4 * g4 + 2] * inv, oacc[db][qi][4 * g4 + 3] * inv);
;                     *(u32x2*)(orow + 32 * db + 8 * g4 + 4 * hl) = w;
;                 }
;         }
.LBB0_455:
	v_and_b32_e32 v67, 64, v195
	v_xor_b32_e32 v66, 32, v195
	v_add_u32_e32 v67, 64, v67
	v_cmp_lt_i32_e32 vcc, v66, v67
	s_lshl_b32 s6, s35, 1
	s_add_i32 s34, s34, s24
	v_cndmask_b32_e32 v66, v195, v66, vcc
	v_lshlrev_b32_e32 v70, 2, v66
	ds_bpermute_b32 v66, v70, v196
	ds_bpermute_b32 v220, v70, v1
	s_cmpk_gt_i32 s34, 0x1ff
	s_waitcnt lgkmcnt(0)
	v_add_f32_e32 v68, v196, v66
	v_add_f32_e32 v1, v1, v220
	v_div_scale_f32 v69, s[4:5], v68, v68, 1.0
	v_rcp_f32_e32 v71, v69
	v_div_scale_f32 v72, vcc, 1.0, v68, 1.0
	v_lshl_add_u64 v[66:67], v[164:165], 0, s[6:7]
	v_fma_f32 v73, -v69, v71, 1.0
	v_fmac_f32_e32 v71, v73, v71
	v_mul_f32_e32 v73, v72, v71
	v_fma_f32 v74, -v69, v73, v72
	v_fmac_f32_e32 v73, v74, v71
	v_fma_f32 v69, -v69, v73, v72
	v_div_fmas_f32 v69, v69, v71, v73
	v_div_fixup_f32 v71, v69, v68, 1.0
	v_div_scale_f32 v224, s[4:5], v1, v1, 1.0
	v_rcp_f32_e32 v225, v224
	v_div_scale_f32 v221, vcc, 1.0, v1, 1.0
	v_lshlrev_b64 v[226:227], 10, v[176:177]
	v_fma_f32 v223, -v224, v225, 1.0
	v_fmac_f32_e32 v225, v223, v225
	v_mul_f32_e32 v222, v221, v225
	v_fma_f32 v223, -v224, v222, v221
	v_fmac_f32_e32 v222, v223, v225
	v_fma_f32 v221, -v224, v222, v221
	v_div_fmas_f32 v221, v221, v225, v222
	v_div_fixup_f32 v1, v221, v1, 1.0
	v_lshl_add_u64 v[226:227], v[66:67], 0, v[226:227]
	v_lshlrev_b64 v[228:229], 10, v[174:175]
	v_lshl_add_u64 v[228:229], v[66:67], 0, v[228:229]
	v_and_b32_e32 v230, 32, v195
	v_lshrrev_b32_e32 v230, 2, v230
	v_mov_b32_e32 v231, 0
	v_lshl_add_u64 v[226:227], v[226:227], 0, v[230:231]
	v_lshl_add_u64 v[228:229], v[228:229], 0, v[230:231]
	v_mul_f32_e32 v34, v34, v71
	v_mul_f32_e32 v35, v35, v71
	v_mul_f32_e32 v36, v36, v71
	v_mul_f32_e32 v37, v37, v71
	v_mul_f32_e32 v38, v38, v71
	v_mul_f32_e32 v39, v39, v71
	v_mul_f32_e32 v40, v40, v71
	v_mul_f32_e32 v41, v41, v71
	v_cvt_pk_bf16_f32 v34, v34, v35
	v_cvt_pk_bf16_f32 v35, v36, v37
	v_cvt_pk_bf16_f32 v36, v38, v39
	v_cvt_pk_bf16_f32 v37, v40, v41
	s_nop 1
	v_permlane32_swap_b32_e32 v34, v36
	v_permlane32_swap_b32_e32 v35, v37
	global_store_dwordx4 v[226:227], v[34:37], off offset:64
	v_mul_f32_e32 v42, v42, v71
	v_mul_f32_e32 v43, v43, v71
	v_mul_f32_e32 v44, v44, v71
	v_mul_f32_e32 v45, v45, v71
	v_mul_f32_e32 v46, v46, v71
	v_mul_f32_e32 v47, v47, v71
	v_mul_f32_e32 v48, v48, v71
	v_mul_f32_e32 v49, v49, v71
	v_cvt_pk_bf16_f32 v42, v42, v43
	v_cvt_pk_bf16_f32 v43, v44, v45
	v_cvt_pk_bf16_f32 v44, v46, v47
	v_cvt_pk_bf16_f32 v45, v48, v49
	s_nop 1
	v_permlane32_swap_b32_e32 v42, v44
	v_permlane32_swap_b32_e32 v43, v45
	global_store_dwordx4 v[226:227], v[42:45], off offset:96
	v_mul_f32_e32 v50, v50, v71
	v_mul_f32_e32 v51, v51, v71
	v_mul_f32_e32 v52, v52, v71
	v_mul_f32_e32 v53, v53, v71
	v_mul_f32_e32 v54, v54, v71
	v_mul_f32_e32 v55, v55, v71
	v_mul_f32_e32 v56, v56, v71
	v_mul_f32_e32 v57, v57, v71
	v_cvt_pk_bf16_f32 v50, v50, v51
	v_cvt_pk_bf16_f32 v51, v52, v53
	v_cvt_pk_bf16_f32 v52, v54, v55
	v_cvt_pk_bf16_f32 v53, v56, v57
	s_nop 1
	v_permlane32_swap_b32_e32 v50, v52
	v_permlane32_swap_b32_e32 v51, v53
	global_store_dwordx4 v[226:227], v[50:53], off
	v_mul_f32_e32 v58, v58, v71
	v_mul_f32_e32 v59, v59, v71
	v_mul_f32_e32 v60, v60, v71
	v_mul_f32_e32 v61, v61, v71
	v_mul_f32_e32 v62, v62, v71
	v_mul_f32_e32 v63, v63, v71
	v_mul_f32_e32 v64, v64, v71
	v_mul_f32_e32 v65, v65, v71
	v_cvt_pk_bf16_f32 v58, v58, v59
	v_cvt_pk_bf16_f32 v59, v60, v61
	v_cvt_pk_bf16_f32 v60, v62, v63
	v_cvt_pk_bf16_f32 v61, v64, v65
	s_nop 1
	v_permlane32_swap_b32_e32 v58, v60
	v_permlane32_swap_b32_e32 v59, v61
	global_store_dwordx4 v[226:227], v[58:61], off offset:32
	v_mul_f32_e32 v18, v18, v1
	v_mul_f32_e32 v19, v19, v1
	v_mul_f32_e32 v20, v20, v1
	v_mul_f32_e32 v21, v21, v1
	v_mul_f32_e32 v22, v22, v1
	v_mul_f32_e32 v23, v23, v1
	v_mul_f32_e32 v24, v24, v1
	v_mul_f32_e32 v25, v25, v1
	v_cvt_pk_bf16_f32 v18, v18, v19
	v_cvt_pk_bf16_f32 v19, v20, v21
	v_cvt_pk_bf16_f32 v20, v22, v23
	v_cvt_pk_bf16_f32 v21, v24, v25
	s_nop 1
	v_permlane32_swap_b32_e32 v18, v20
	v_permlane32_swap_b32_e32 v19, v21
	global_store_dwordx4 v[228:229], v[18:21], off
	v_mul_f32_e32 v26, v26, v1
	v_mul_f32_e32 v27, v27, v1
	v_mul_f32_e32 v28, v28, v1
	v_mul_f32_e32 v29, v29, v1
	v_mul_f32_e32 v30, v30, v1
	v_mul_f32_e32 v31, v31, v1
	v_mul_f32_e32 v32, v32, v1
	v_mul_f32_e32 v33, v33, v1
	v_cvt_pk_bf16_f32 v26, v26, v27
	v_cvt_pk_bf16_f32 v27, v28, v29
	v_cvt_pk_bf16_f32 v28, v30, v31
	v_cvt_pk_bf16_f32 v29, v32, v33
	s_nop 1
	v_permlane32_swap_b32_e32 v26, v28
	v_permlane32_swap_b32_e32 v27, v29
	global_store_dwordx4 v[228:229], v[26:29], off offset:32
	v_mul_f32_e32 v2, v2, v1
	v_mul_f32_e32 v3, v3, v1
	v_mul_f32_e32 v4, v4, v1
	v_mul_f32_e32 v5, v5, v1
	v_mul_f32_e32 v6, v6, v1
	v_mul_f32_e32 v7, v7, v1
	v_mul_f32_e32 v8, v8, v1
	v_mul_f32_e32 v9, v9, v1
	v_cvt_pk_bf16_f32 v2, v2, v3
	v_cvt_pk_bf16_f32 v3, v4, v5
	v_cvt_pk_bf16_f32 v4, v6, v7
	v_cvt_pk_bf16_f32 v5, v8, v9
	s_nop 1
	v_permlane32_swap_b32_e32 v2, v4
	v_permlane32_swap_b32_e32 v3, v5
	global_store_dwordx4 v[228:229], v[2:5], off offset:64
	v_mul_f32_e32 v10, v10, v1
	v_mul_f32_e32 v11, v11, v1
	v_mul_f32_e32 v12, v12, v1
	v_mul_f32_e32 v13, v13, v1
	v_mul_f32_e32 v14, v14, v1
	v_mul_f32_e32 v15, v15, v1
	v_mul_f32_e32 v16, v16, v1
	v_mul_f32_e32 v17, v17, v1
	v_cvt_pk_bf16_f32 v10, v10, v11
	v_cvt_pk_bf16_f32 v11, v12, v13
	v_cvt_pk_bf16_f32 v12, v14, v15
	v_cvt_pk_bf16_f32 v13, v16, v17
	s_nop 1
	v_permlane32_swap_b32_e32 v10, v12
	v_permlane32_swap_b32_e32 v11, v13
	global_store_dwordx4 v[228:229], v[10:13], off offset:96
	s_cbranch_scc1 .LBB0_489
